# v23 + per-tile branch targets of the GEMM phases (unit-loop headers, epilogue entries, pool K-loop head) aligned to 64 B
# speedup vs baseline: 1.0058x; 1.0058x over previous
; template <class Epi, class Sched, bool ALIGN_EPI = false>
; __device__ __forceinline__ void gemm_phase8(PG8_LAS unsigned char* lds, const Gemm g, const Sched& S, const Epi& E) {
;     ...
;     for (;;) {
;         const bool has_next = S.next(ui + 1, nxt);
;         const size_t nko = (has_next && nxt.kp > 0) ? (size_t)nxt.kp * g.kpiece : 0;
;         const char* nA = has_next ? (const char*)g.A + (size_t)nxt.pm * tstepA + (size_t)nxt.pn * astep + nko : cA; const char* nB = has_next ? (const char*)g.Bt + (size_t)nxt.pn * tstepB + nko : cB;
.LBB0_321:
	s_andn2_b64 vcc, exec, s[2:3]
	s_mov_b32 s60, s12
	s_mov_b32 s20, s14
	s_mov_b64 s[24:25], s[18:19]
	s_mov_b64 s[22:23], s[16:17]
	s_cbranch_vccz .LBB0_331
	.p2align	6

; #define PG8_STAGE(bufoff, gbase, voff) do { _Pragma("unroll") for (int _i = 0; _i < 2; ++_i) \
;         __builtin_amdgcn_global_load_lds((const unsigned*)((const char*)(gbase) + (voff)[_i]), (PG8_LAS unsigned*)(lds + (bufoff) + ldsw + _i * 8192), 16, 0, 0); } while (0)
; #define PG8_LDA(dst, b, h) do { _Pragma("unroll") for (int m = 0; m < 4; ++m) _Pragma("unroll") for (int k = 0; k < 2; ++k) dst[m][k] = *(const PG8_LAS bf16x8*)(lds + PG8_SA(b, h) + aoff + m * 2048 + k * 1024); } while (0)
; #define PG8_LDB(dst, b, h) do { _Pragma("unroll") for (int n = 0; n < 2; ++n) _Pragma("unroll") for (int k = 0; k < 2; ++k) dst[n][k] = *(const PG8_LAS bf16x8*)(lds + PG8_SB(b, h) + boff + n * 2048 + k * 1024); } while (0)
; #define PG8_MMA(ai, bj, At, Bt) do { __builtin_amdgcn_s_setprio(1); _Pragma("unroll") for (int m = 0; m < 4; ++m) _Pragma("unroll") for (int n = 0; n < 2; ++n) _Pragma("unroll") for (int k = 0; k < 2; ++k) \
;         acc[ai][bj][m][n] = __builtin_amdgcn_mfma_f32_16x16x32_bf16(Bt[n][k], At[m][k], acc[ai][bj][m][n], 0, 0, 0); __builtin_amdgcn_s_setprio(0); } while (0)
; #define PG8_WAIT_V(n) asm volatile("s_waitcnt vmcnt(" #n ")" ::: "memory")
; #define PG8_WAIT_L(n) asm volatile("s_waitcnt lgkmcnt(" #n ")" ::: "memory")
; #define PG8_BAR __builtin_amdgcn_s_barrier()
; #define PG8_SCHED __builtin_amdgcn_sched_barrier(0)
; #define PG8_STAGE(bufoff, gbase, voff) do { _Pragma("unroll") for (int _i = 0; _i < 2; ++_i) \
;         __builtin_amdgcn_global_load_lds((const unsigned*)((const char*)(gbase) + (voff)[_i]), (PG8_LAS unsigned*)(lds + (bufoff) + ldsw + _i * 8192), 16, 0, 0); } while (0)
; #define PG8_WAIT_V(n) asm volatile("s_waitcnt vmcnt(" #n ")" ::: "memory")
; template <class Epi, class Sched, bool ALIGN_EPI = false>
; __device__ __forceinline__ void gemm_phase8(PG8_LAS unsigned char* lds, const Gemm g, const Sched& S, const Epi& E) {
;     ...
;             PG8_LDB(B0, 0, 0); PG8_LDB(B1, 0, 1); PG8_SCHED; PG8_LDA(At, 0, 0); PG8_STAGE(PG8_SA(1, 1), a1 + hstepA, voffA);
;             PG8_WAIT_V(8); PG8_WAIT_L(0); PG8_BAR; PG8_MMA(0, 0, At, B0); PG8_MMA(0, 1, At, B1); PG8_BAR; PG8_SCHED;
;             PG8_LDA(At, 0, 1); PG8_STAGE(PG8_SB(0, 0), b2, voffB); PG8_STAGE(PG8_SB(0, 1), b2 + hstepB, voffB); PG8_STAGE(PG8_SA(0, 0), a2, voffA);
;             PG8_WAIT_V(8); PG8_WAIT_L(0); PG8_BAR; PG8_MMA(1, 0, At, B0); PG8_MMA(1, 1, At, B1); PG8_BAR; PG8_SCHED;
.LBB0_325:
	ds_read_b128 v[18:21], v191
	ds_read_b128 v[26:29], v191 offset:2048
	ds_read_b128 v[22:25], v192
	ds_read_b128 v[30:33], v192 offset:2048
	ds_read_b128 v[2:5], v193
	ds_read_b128 v[10:13], v193 offset:2048
	ds_read_b128 v[6:9], v194
	ds_read_b128 v[14:17], v194 offset:2048
	s_add_u32 s24, s22, 0xfffc0080
	s_addc_u32 s25, s23, -1
	s_cmp_eq_u32 s65, 12
	s_cselect_b32 s27, s15, s25
	s_cselect_b32 s26, s61, s24
	s_cselect_b32 s25, s13, s64
	s_cselect_b32 s24, s62, s63
	s_add_i32 m0, s21, 0xc000
	ds_read_b128 v[178:181], v195
	ds_read_b128 v[198:201], v195 offset:2048
	ds_read_b128 v[182:185], v196
	ds_read_b128 v[202:205], v196 offset:2048
	ds_read_b128 v[206:209], v195 offset:4096
	ds_read_b128 v[214:217], v195 offset:6144
	ds_read_b128 v[210:213], v196 offset:4096
	ds_read_b128 v[218:221], v196 offset:6144
	global_load_lds_dwordx4 v170, s[22:23]
	s_add_i32 m0, s21, 0xe000
	s_nop 0
	global_load_lds_dwordx4 v172, s[22:23]
	s_waitcnt vmcnt(8)
	s_waitcnt lgkmcnt(0)
	s_barrier
	s_setprio 1
	s_waitcnt lgkmcnt(0)
	v_mfma_scale_f32_16x16x128_f8f6f4 v[158:161], v[18:25], v[178:185], v[158:161], v1, v186 op_sel_hi:[0,0,0]
	v_mfma_scale_f32_16x16x128_f8f6f4 v[150:153], v[26:33], v[178:185], v[150:153], v1, v186 op_sel_hi:[0,0,0]
	v_mfma_scale_f32_16x16x128_f8f6f4 v[142:145], v[18:25], v[198:205], v[142:145], v1, v186 op_sel_hi:[0,0,0]
	v_mfma_scale_f32_16x16x128_f8f6f4 v[134:137], v[26:33], v[198:205], v[134:137], v1, v186 op_sel_hi:[0,0,0]
	v_mfma_scale_f32_16x16x128_f8f6f4 v[126:129], v[18:25], v[206:213], v[126:129], v1, v186 op_sel_hi:[0,0,0]
	v_mfma_scale_f32_16x16x128_f8f6f4 v[118:121], v[26:33], v[206:213], v[118:121], v1, v186 op_sel_hi:[0,0,0]
	v_mfma_scale_f32_16x16x128_f8f6f4 v[110:113], v[18:25], v[214:221], v[110:113], v1, v186 op_sel_hi:[0,0,0]
	v_mfma_scale_f32_16x16x128_f8f6f4 v[102:105], v[26:33], v[214:221], v[102:105], v1, v186 op_sel_hi:[0,0,0]
	s_setprio 0
	s_setprio 1
	v_mfma_scale_f32_16x16x128_f8f6f4 v[154:157], v[2:9], v[178:185], v[154:157], v1, v186 op_sel_hi:[0,0,0]
	v_mfma_scale_f32_16x16x128_f8f6f4 v[146:149], v[10:17], v[178:185], v[146:149], v1, v186 op_sel_hi:[0,0,0]
	v_mfma_scale_f32_16x16x128_f8f6f4 v[138:141], v[2:9], v[198:205], v[138:141], v1, v186 op_sel_hi:[0,0,0]
	v_mfma_scale_f32_16x16x128_f8f6f4 v[130:133], v[10:17], v[198:205], v[130:133], v1, v186 op_sel_hi:[0,0,0]
	v_mfma_scale_f32_16x16x128_f8f6f4 v[122:125], v[2:9], v[206:213], v[122:125], v1, v186 op_sel_hi:[0,0,0]
	v_mfma_scale_f32_16x16x128_f8f6f4 v[114:117], v[10:17], v[206:213], v[114:117], v1, v186 op_sel_hi:[0,0,0]
	v_mfma_scale_f32_16x16x128_f8f6f4 v[106:109], v[2:9], v[214:221], v[106:109], v1, v186 op_sel_hi:[0,0,0]
	v_mfma_scale_f32_16x16x128_f8f6f4 v[98:101], v[10:17], v[214:221], v[98:101], v1, v186 op_sel_hi:[0,0,0]
	s_setprio 0
	s_barrier
	s_add_i32 s66, s57, s30
	s_mov_b32 m0, s66
	ds_read_b128 v[198:201], v195 offset:16384
	ds_read_b128 v[206:209], v195 offset:18432
	ds_read_b128 v[202:205], v196 offset:16384
	ds_read_b128 v[210:213], v196 offset:18432
	ds_read_b128 v[214:217], v195 offset:20480
	ds_read_b128 v[222:225], v195 offset:22528
	ds_read_b128 v[218:221], v196 offset:20480
	ds_read_b128 v[226:229], v196 offset:22528
	global_load_lds_dwordx4 v164, s[24:25]
	s_add_i32 m0, s66, 0x2000
	s_add_u32 s66, s24, 0x40000
	s_addc_u32 s67, s25, 0
	s_add_i32 s72, s58, s30
	global_load_lds_dwordx4 v168, s[24:25]
	s_mov_b32 m0, s72
	s_nop 0
	global_load_lds_dwordx4 v164, s[66:67]
	s_add_i32 m0, s72, 0x2000
	s_nop 0
	global_load_lds_dwordx4 v168, s[66:67]
	s_mov_b32 m0, s21
	s_nop 0
	global_load_lds_dwordx4 v162, s[26:27]
	s_mov_b32 m0, s34
	s_nop 0
	global_load_lds_dwordx4 v166, s[26:27]
	s_waitcnt vmcnt(8)
	s_waitcnt lgkmcnt(0)
	s_barrier
	s_setprio 1
	s_waitcnt lgkmcnt(0)
	v_mfma_scale_f32_16x16x128_f8f6f4 v[94:97], v[18:25], v[198:205], v[94:97], v1, v186 op_sel_hi:[0,0,0]
	v_mfma_scale_f32_16x16x128_f8f6f4 v[86:89], v[26:33], v[198:205], v[86:89], v1, v186 op_sel_hi:[0,0,0]
	v_mfma_scale_f32_16x16x128_f8f6f4 v[78:81], v[18:25], v[206:213], v[78:81], v1, v186 op_sel_hi:[0,0,0]
	v_mfma_scale_f32_16x16x128_f8f6f4 v[70:73], v[26:33], v[206:213], v[70:73], v1, v186 op_sel_hi:[0,0,0]
	v_mfma_scale_f32_16x16x128_f8f6f4 v[62:65], v[18:25], v[214:221], v[62:65], v1, v186 op_sel_hi:[0,0,0]
	v_mfma_scale_f32_16x16x128_f8f6f4 v[54:57], v[26:33], v[214:221], v[54:57], v1, v186 op_sel_hi:[0,0,0]
	v_mfma_scale_f32_16x16x128_f8f6f4 v[46:49], v[18:25], v[222:229], v[46:49], v1, v186 op_sel_hi:[0,0,0]
	v_mfma_scale_f32_16x16x128_f8f6f4 v[38:41], v[26:33], v[222:229], v[38:41], v1, v186 op_sel_hi:[0,0,0]
	s_setprio 0
	s_setprio 1
	v_mfma_scale_f32_16x16x128_f8f6f4 v[90:93], v[2:9], v[198:205], v[90:93], v1, v186 op_sel_hi:[0,0,0]
	v_mfma_scale_f32_16x16x128_f8f6f4 v[82:85], v[10:17], v[198:205], v[82:85], v1, v186 op_sel_hi:[0,0,0]
	v_mfma_scale_f32_16x16x128_f8f6f4 v[74:77], v[2:9], v[206:213], v[74:77], v1, v186 op_sel_hi:[0,0,0]
	v_mfma_scale_f32_16x16x128_f8f6f4 v[66:69], v[10:17], v[206:213], v[66:69], v1, v186 op_sel_hi:[0,0,0]
	v_mfma_scale_f32_16x16x128_f8f6f4 v[58:61], v[2:9], v[214:221], v[58:61], v1, v186 op_sel_hi:[0,0,0]
	v_mfma_scale_f32_16x16x128_f8f6f4 v[50:53], v[10:17], v[214:221], v[50:53], v1, v186 op_sel_hi:[0,0,0]
	v_mfma_scale_f32_16x16x128_f8f6f4 v[42:45], v[2:9], v[222:229], v[42:45], v1, v186 op_sel_hi:[0,0,0]
	v_mfma_scale_f32_16x16x128_f8f6f4 v[34:37], v[10:17], v[222:229], v[34:37], v1, v186 op_sel_hi:[0,0,0]
	s_setprio 0
	s_barrier
; #define PG8_STAGE(bufoff, gbase, voff) do { _Pragma("unroll") for (int _i = 0; _i < 2; ++_i) \
;         __builtin_amdgcn_global_load_lds((const unsigned*)((const char*)(gbase) + (voff)[_i]), (PG8_LAS unsigned*)(lds + (bufoff) + ldsw + _i * 8192), 16, 0, 0); } while (0)
; #define PG8_LDA(dst, b, h) do { _Pragma("unroll") for (int m = 0; m < 4; ++m) _Pragma("unroll") for (int k = 0; k < 2; ++k) dst[m][k] = *(const PG8_LAS bf16x8*)(lds + PG8_SA(b, h) + aoff + m * 2048 + k * 1024); } while (0)
; #define PG8_LDB(dst, b, h) do { _Pragma("unroll") for (int n = 0; n < 2; ++n) _Pragma("unroll") for (int k = 0; k < 2; ++k) dst[n][k] = *(const PG8_LAS bf16x8*)(lds + PG8_SB(b, h) + boff + n * 2048 + k * 1024); } while (0)
; #define PG8_MMA(ai, bj, At, Bt) do { __builtin_amdgcn_s_setprio(1); _Pragma("unroll") for (int m = 0; m < 4; ++m) _Pragma("unroll") for (int n = 0; n < 2; ++n) _Pragma("unroll") for (int k = 0; k < 2; ++k) \
;         acc[ai][bj][m][n] = __builtin_amdgcn_mfma_f32_16x16x32_bf16(Bt[n][k], At[m][k], acc[ai][bj][m][n], 0, 0, 0); __builtin_amdgcn_s_setprio(0); } while (0)
; #define PG8_WAIT_V(n) asm volatile("s_waitcnt vmcnt(" #n ")" ::: "memory")
; #define PG8_WAIT_L(n) asm volatile("s_waitcnt lgkmcnt(" #n ")" ::: "memory")
; #define PG8_BAR __builtin_amdgcn_s_barrier()
; #define PG8_SCHED __builtin_amdgcn_sched_barrier(0)
; #define PG8_STAGE(bufoff, gbase, voff) do { _Pragma("unroll") for (int _i = 0; _i < 2; ++_i) \
;         __builtin_amdgcn_global_load_lds((const unsigned*)((const char*)(gbase) + (voff)[_i]), (PG8_LAS unsigned*)(lds + (bufoff) + ldsw + _i * 8192), 16, 0, 0); } while (0)
; #define PG8_BAR __builtin_amdgcn_s_barrier()
; template <class Epi, class Sched, bool ALIGN_EPI = false>
; __device__ __forceinline__ void gemm_phase8(PG8_LAS unsigned char* lds, const Gemm g, const Sched& S, const Epi& E) {
;     ...
;             PG8_LDB(B0, 1, 0); PG8_LDB(B1, 1, 1); PG8_SCHED; PG8_LDA(At, 1, 0); PG8_STAGE(PG8_SA(0, 1), a2 + hstepA, voffA);
;             PG8_WAIT_V(8); PG8_WAIT_L(0); PG8_BAR; PG8_MMA(0, 0, At, B0); PG8_MMA(0, 1, At, B1); PG8_BAR; PG8_SCHED;
;             PG8_LDA(At, 1, 1); PG8_STAGE(PG8_SB(1, 0), b3, voffB); PG8_STAGE(PG8_SB(1, 1), b3 + hstepB, voffB); PG8_STAGE(PG8_SA(1, 0), a3, voffA);
;             PG8_WAIT_V(8); PG8_WAIT_L(0); PG8_BAR; PG8_MMA(1, 0, At, B0); PG8_MMA(1, 1, At, B1); PG8_BAR; PG8_SCHED;
;         }
	s_add_i32 s66, 0, 0x18000
	s_add_i32 s67, 0, 0x1c000
	v_add_u32_e32 v6, s66, v187
	v_add_u32_e32 v14, s66, v188
	v_add_u32_e32 v22, s67, v187
	v_add_u32_e32 v30, s67, v188
	ds_read_b128 v[2:5], v6
	ds_read_b128 v[10:13], v6 offset:2048
	ds_read_b128 v[6:9], v14
	ds_read_b128 v[14:17], v14 offset:2048
	ds_read_b128 v[18:21], v22
	ds_read_b128 v[26:29], v22 offset:2048
	ds_read_b128 v[22:25], v30
	ds_read_b128 v[30:33], v30 offset:2048
	s_add_u32 s26, s26, 0x40000
	s_addc_u32 s27, s27, 0
	s_mov_b32 m0, s35
	ds_read_b128 v[198:201], v195 offset:32768
	ds_read_b128 v[206:209], v195 offset:34816
	ds_read_b128 v[202:205], v196 offset:32768
	ds_read_b128 v[210:213], v196 offset:34816
	ds_read_b128 v[214:217], v195 offset:36864
	ds_read_b128 v[222:225], v195 offset:38912
	ds_read_b128 v[218:221], v196 offset:36864
	ds_read_b128 v[226:229], v196 offset:38912
	global_load_lds_dwordx4 v162, s[26:27]
	s_mov_b32 m0, s52
	s_nop 0
	global_load_lds_dwordx4 v166, s[26:27]
	s_waitcnt vmcnt(8)
	s_waitcnt lgkmcnt(0)
	s_barrier
	s_setprio 1
	s_waitcnt lgkmcnt(0)
	v_mfma_scale_f32_16x16x128_f8f6f4 v[158:161], v[2:9], v[198:205], v[158:161], v1, v186 op_sel_hi:[0,0,0]
	v_mfma_scale_f32_16x16x128_f8f6f4 v[150:153], v[10:17], v[198:205], v[150:153], v1, v186 op_sel_hi:[0,0,0]
	v_mfma_scale_f32_16x16x128_f8f6f4 v[142:145], v[2:9], v[206:213], v[142:145], v1, v186 op_sel_hi:[0,0,0]
	v_mfma_scale_f32_16x16x128_f8f6f4 v[134:137], v[10:17], v[206:213], v[134:137], v1, v186 op_sel_hi:[0,0,0]
	v_mfma_scale_f32_16x16x128_f8f6f4 v[126:129], v[2:9], v[214:221], v[126:129], v1, v186 op_sel_hi:[0,0,0]
	v_mfma_scale_f32_16x16x128_f8f6f4 v[118:121], v[10:17], v[214:221], v[118:121], v1, v186 op_sel_hi:[0,0,0]
	v_mfma_scale_f32_16x16x128_f8f6f4 v[110:113], v[2:9], v[222:229], v[110:113], v1, v186 op_sel_hi:[0,0,0]
	v_mfma_scale_f32_16x16x128_f8f6f4 v[102:105], v[10:17], v[222:229], v[102:105], v1, v186 op_sel_hi:[0,0,0]
	s_setprio 0
	s_setprio 1
	v_mfma_scale_f32_16x16x128_f8f6f4 v[154:157], v[18:25], v[198:205], v[154:157], v1, v186 op_sel_hi:[0,0,0]
	v_mfma_scale_f32_16x16x128_f8f6f4 v[146:149], v[26:33], v[198:205], v[146:149], v1, v186 op_sel_hi:[0,0,0]
	v_mfma_scale_f32_16x16x128_f8f6f4 v[138:141], v[18:25], v[206:213], v[138:141], v1, v186 op_sel_hi:[0,0,0]
	v_mfma_scale_f32_16x16x128_f8f6f4 v[130:133], v[26:33], v[206:213], v[130:133], v1, v186 op_sel_hi:[0,0,0]
	v_mfma_scale_f32_16x16x128_f8f6f4 v[122:125], v[18:25], v[214:221], v[122:125], v1, v186 op_sel_hi:[0,0,0]
	v_mfma_scale_f32_16x16x128_f8f6f4 v[114:117], v[26:33], v[214:221], v[114:117], v1, v186 op_sel_hi:[0,0,0]
	v_mfma_scale_f32_16x16x128_f8f6f4 v[106:109], v[18:25], v[222:229], v[106:109], v1, v186 op_sel_hi:[0,0,0]
	v_mfma_scale_f32_16x16x128_f8f6f4 v[98:101], v[26:33], v[222:229], v[98:101], v1, v186 op_sel_hi:[0,0,0]
	s_setprio 0
	s_barrier
	s_add_i32 s101, s66, s30
	s_add_u32 s98, s24, s8
	s_addc_u32 s99, s25, s9
	s_mov_b32 m0, s101
	ds_read_b128 v[198:201], v195 offset:49152
	ds_read_b128 v[206:209], v195 offset:51200
	ds_read_b128 v[202:205], v196 offset:49152
	ds_read_b128 v[210:213], v196 offset:51200
	ds_read_b128 v[214:217], v195 offset:53248
	ds_read_b128 v[222:225], v195 offset:55296
	ds_read_b128 v[218:221], v196 offset:53248
	ds_read_b128 v[226:229], v196 offset:55296
	global_load_lds_dwordx4 v164, s[98:99]
	s_add_i32 m0, s101, 0x2000
	s_add_u32 s24, s24, 0x40080
	s_addc_u32 s25, s25, 0
	s_add_i32 s101, s67, s30
	global_load_lds_dwordx4 v168, s[98:99]
	s_add_u32 s98, s26, s8
	s_addc_u32 s99, s27, s9
	s_sub_u32 s98, s98, 0x40000
	s_subb_u32 s99, s99, 0
	s_mov_b32 m0, s101
	s_nop 0
	global_load_lds_dwordx4 v164, s[24:25]
	s_add_i32 m0, s101, 0x2000
	s_nop 0
	global_load_lds_dwordx4 v168, s[24:25]
	s_mov_b32 m0, s55
	s_nop 0
	global_load_lds_dwordx4 v162, s[98:99]
	s_mov_b32 m0, s56
	s_nop 0
	global_load_lds_dwordx4 v166, s[98:99]
	s_waitcnt vmcnt(8)
	s_waitcnt lgkmcnt(0)
	s_barrier
	s_setprio 1
	s_waitcnt lgkmcnt(0)
	v_mfma_scale_f32_16x16x128_f8f6f4 v[94:97], v[2:9], v[198:205], v[94:97], v1, v186 op_sel_hi:[0,0,0]
	v_mfma_scale_f32_16x16x128_f8f6f4 v[86:89], v[10:17], v[198:205], v[86:89], v1, v186 op_sel_hi:[0,0,0]
	v_mfma_scale_f32_16x16x128_f8f6f4 v[78:81], v[2:9], v[206:213], v[78:81], v1, v186 op_sel_hi:[0,0,0]
	v_mfma_scale_f32_16x16x128_f8f6f4 v[70:73], v[10:17], v[206:213], v[70:73], v1, v186 op_sel_hi:[0,0,0]
	v_mfma_scale_f32_16x16x128_f8f6f4 v[62:65], v[2:9], v[214:221], v[62:65], v1, v186 op_sel_hi:[0,0,0]
	v_mfma_scale_f32_16x16x128_f8f6f4 v[54:57], v[10:17], v[214:221], v[54:57], v1, v186 op_sel_hi:[0,0,0]
	v_mfma_scale_f32_16x16x128_f8f6f4 v[46:49], v[2:9], v[222:229], v[46:49], v1, v186 op_sel_hi:[0,0,0]
	v_mfma_scale_f32_16x16x128_f8f6f4 v[38:41], v[10:17], v[222:229], v[38:41], v1, v186 op_sel_hi:[0,0,0]
	s_setprio 0
	s_setprio 1
	v_mfma_scale_f32_16x16x128_f8f6f4 v[90:93], v[18:25], v[198:205], v[90:93], v1, v186 op_sel_hi:[0,0,0]
	v_mfma_scale_f32_16x16x128_f8f6f4 v[82:85], v[26:33], v[198:205], v[82:85], v1, v186 op_sel_hi:[0,0,0]
	v_mfma_scale_f32_16x16x128_f8f6f4 v[74:77], v[18:25], v[206:213], v[74:77], v1, v186 op_sel_hi:[0,0,0]
	v_mfma_scale_f32_16x16x128_f8f6f4 v[66:69], v[26:33], v[206:213], v[66:69], v1, v186 op_sel_hi:[0,0,0]
	v_mfma_scale_f32_16x16x128_f8f6f4 v[58:61], v[18:25], v[214:221], v[58:61], v1, v186 op_sel_hi:[0,0,0]
	v_mfma_scale_f32_16x16x128_f8f6f4 v[50:53], v[26:33], v[214:221], v[50:53], v1, v186 op_sel_hi:[0,0,0]
	v_mfma_scale_f32_16x16x128_f8f6f4 v[42:45], v[18:25], v[222:229], v[42:45], v1, v186 op_sel_hi:[0,0,0]
	v_mfma_scale_f32_16x16x128_f8f6f4 v[34:37], v[26:33], v[222:229], v[34:37], v1, v186 op_sel_hi:[0,0,0]
	s_setprio 0
	s_barrier
	s_add_i32 s65, s65, 2
	s_add_u32 s22, s22, 0x100
	s_addc_u32 s23, s23, 0
	s_add_u32 s63, s63, 0x100
	s_addc_u32 s64, s64, 0
	s_cmp_gt_u32 s65, 13
	s_cbranch_scc0 .LBB0_325
	s_and_b64 vcc, exec, s[10:11]
	s_cbranch_vccz .LBB0_328
	s_barrier
	.p2align	6

; template <class Epi, class Sched, bool ALIGN_EPI = false>
; __device__ __forceinline__ void gemm_phase8(PG8_LAS unsigned char* lds, const Gemm g, const Sched& S, const Epi& E) {
;     ...
;     for (;;) {
;         const bool has_next = S.next(ui + 1, nxt);
;         const size_t nko = (has_next && nxt.kp > 0) ? (size_t)nxt.kp * g.kpiece : 0;
;         const char* nA = has_next ? (const char*)g.A + (size_t)nxt.pm * tstepA + (size_t)nxt.pn * astep + nko : cA; const char* nB = has_next ? (const char*)g.Bt + (size_t)nxt.pn * tstepB + nko : cB;
.LBB0_492:
	s_andn2_b64 vcc, exec, s[2:3]
	s_mov_b32 s75, s73
	s_mov_b32 s80, s74
	s_mov_b32 s24, s0
	s_mov_b64 s[30:31], s[22:23]
	s_mov_b64 s[28:29], s[20:21]
	s_cbranch_vccz .LBB0_512
	.p2align	6

; template <class Epi, class Sched, bool ALIGN_EPI = false>
; __device__ __forceinline__ void gemm_phase(PG8_LAS unsigned char* lds, const Gemm g, const Sched& S, const Epi& E) {
;     ...
;     for (;;) {
;         const bool has_next = S.next(ui + 1, nxt);
;         const size_t nko = (has_next && nxt.kp > 0) ? (size_t)nxt.kp * g.kpiece * 2 : 0;
;         const char* nA = has_next ? (const char*)g.A + (size_t)nxt.pm * tstepA + (size_t)nxt.pn * astep + nko : cA; const char* nB = has_next ? (const char*)g.Bt + (size_t)nxt.pn * tstepB + nko : cB;
.LBB0_730:
	s_andn2_b64 vcc, exec, s[2:3]
	s_mov_b32 s33, s24
	s_mov_b32 s12, s26
	s_mov_b64 s[34:35], s[30:31]
	s_mov_b64 s[52:53], s[28:29]
	s_cbranch_vccz .LBB0_748
	.p2align	6

; template <class Epi, class Sched, bool ALIGN_EPI = false>
; __device__ __forceinline__ void gemm_phase(PG8_LAS unsigned char* lds, const Gemm g, const Sched& S, const Epi& E) {
;     ...
;     for (;;) {
;         const bool has_next = S.next(ui + 1, nxt);
;         const size_t nko = (has_next && nxt.kp > 0) ? (size_t)nxt.kp * g.kpiece * 2 : 0;
;         const char* nA = has_next ? (const char*)g.A + (size_t)nxt.pm * tstepA + (size_t)nxt.pn * astep + nko : cA; const char* nB = has_next ? (const char*)g.Bt + (size_t)nxt.pn * tstepB + nko : cB;
.LBB0_1004:
	s_and_b64 vcc, exec, s[2:3]
	s_mov_b32 s66, s16
	s_mov_b32 s24, s18
	s_mov_b64 s[28:29], s[22:23]
	s_mov_b64 s[26:27], s[20:21]
	s_cbranch_vccnz .LBB0_1012
	.p2align	6

; template <class Epi, class Sched, bool ALIGN_EPI = false>
; __device__ __forceinline__ void gemm_phase8(PG8_LAS unsigned char* lds, const Gemm g, const Sched& S, const Epi& E) {
;     ...
;     for (;;) {
;         const bool has_next = S.next(ui + 1, nxt);
;         const size_t nko = (has_next && nxt.kp > 0) ? (size_t)nxt.kp * g.kpiece : 0;
;         const char* nA = has_next ? (const char*)g.A + (size_t)nxt.pm * tstepA + (size_t)nxt.pn * astep + nko : cA; const char* nB = has_next ? (const char*)g.Bt + (size_t)nxt.pn * tstepB + nko : cB;
.LBB0_1181:
	s_andn2_b64 vcc, exec, s[22:23]
	s_mov_b32 s28, s18
	s_mov_b32 s52, s20
	s_mov_b32 s30, s0
	s_mov_b64 s[34:35], s[26:27]
	s_mov_b64 s[56:57], s[24:25]
	s_cbranch_vccz .LBB0_1197
	.p2align	6

; template <class Epi, class Sched, bool ALIGN_EPI = false>
; __device__ __forceinline__ void gemm_phase8(PG8_LAS unsigned char* lds, const Gemm g, const Sched& S, const Epi& E) {
;     ...
;     for (;;) {
;         const bool has_next = S.next(ui + 1, nxt);
;         const size_t nko = (has_next && nxt.kp > 0) ? (size_t)nxt.kp * g.kpiece : 0;
;         const char* nA = has_next ? (const char*)g.A + (size_t)nxt.pm * tstepA + (size_t)nxt.pn * astep + nko : cA; const char* nB = has_next ? (const char*)g.Bt + (size_t)nxt.pn * tstepB + nko : cB;
.LBB0_1418:
	s_andn2_b64 vcc, exec, s[2:3]
	s_mov_b32 s44, s10
	s_mov_b32 s18, s12
	s_mov_b64 s[22:23], s[16:17]
	s_mov_b64 s[20:21], s[14:15]
	s_cbranch_vccz .LBB0_1428
	.p2align	6

; #define PG8_STAGE(bufoff, gbase, voff) do { _Pragma("unroll") for (int _i = 0; _i < 2; ++_i) \
;         __builtin_amdgcn_global_load_lds((const unsigned*)((const char*)(gbase) + (voff)[_i]), (PG8_LAS unsigned*)(lds + (bufoff) + ldsw + _i * 8192), 16, 0, 0); } while (0)
; #define PG8_LDA(dst, b, h) do { _Pragma("unroll") for (int m = 0; m < 4; ++m) _Pragma("unroll") for (int k = 0; k < 2; ++k) dst[m][k] = *(const PG8_LAS bf16x8*)(lds + PG8_SA(b, h) + aoff + m * 2048 + k * 1024); } while (0)
; #define PG8_LDB(dst, b, h) do { _Pragma("unroll") for (int n = 0; n < 2; ++n) _Pragma("unroll") for (int k = 0; k < 2; ++k) dst[n][k] = *(const PG8_LAS bf16x8*)(lds + PG8_SB(b, h) + boff + n * 2048 + k * 1024); } while (0)
; #define PG8_MMA(ai, bj, At, Bt) do { __builtin_amdgcn_s_setprio(1); _Pragma("unroll") for (int m = 0; m < 4; ++m) _Pragma("unroll") for (int n = 0; n < 2; ++n) _Pragma("unroll") for (int k = 0; k < 2; ++k) \
;         acc[ai][bj][m][n] = __builtin_amdgcn_mfma_f32_16x16x32_bf16(Bt[n][k], At[m][k], acc[ai][bj][m][n], 0, 0, 0); __builtin_amdgcn_s_setprio(0); } while (0)
; #define PG8_WAIT_V(n) asm volatile("s_waitcnt vmcnt(" #n ")" ::: "memory")
; #define PG8_WAIT_L(n) asm volatile("s_waitcnt lgkmcnt(" #n ")" ::: "memory")
; #define PG8_BAR __builtin_amdgcn_s_barrier()
; #define PG8_SCHED __builtin_amdgcn_sched_barrier(0)
; #define PG8_STAGE(bufoff, gbase, voff) do { _Pragma("unroll") for (int _i = 0; _i < 2; ++_i) \
;         __builtin_amdgcn_global_load_lds((const unsigned*)((const char*)(gbase) + (voff)[_i]), (PG8_LAS unsigned*)(lds + (bufoff) + ldsw + _i * 8192), 16, 0, 0); } while (0)
; #define PG8_WAIT_V(n) asm volatile("s_waitcnt vmcnt(" #n ")" ::: "memory")
; template <class Epi, class Sched, bool ALIGN_EPI = false>
; __device__ __forceinline__ void gemm_phase8(PG8_LAS unsigned char* lds, const Gemm g, const Sched& S, const Epi& E) {
;     ...
;             PG8_LDB(B0, 0, 0); PG8_LDB(B1, 0, 1); PG8_SCHED; PG8_LDA(At, 0, 0); PG8_STAGE(PG8_SA(1, 1), a1 + hstepA, voffA);
;             PG8_WAIT_V(8); PG8_WAIT_L(0); PG8_BAR; PG8_MMA(0, 0, At, B0); PG8_MMA(0, 1, At, B1); PG8_BAR; PG8_SCHED;
;             PG8_LDA(At, 0, 1); PG8_STAGE(PG8_SB(0, 0), b2, voffB); PG8_STAGE(PG8_SB(0, 1), b2 + hstepB, voffB); PG8_STAGE(PG8_SA(0, 0), a2, voffA);
;             PG8_WAIT_V(8); PG8_WAIT_L(0); PG8_BAR; PG8_MMA(1, 0, At, B0); PG8_MMA(1, 1, At, B1); PG8_BAR; PG8_SCHED;
.LBB0_1422:
	ds_read_b128 v[18:21], v191
	ds_read_b128 v[26:29], v191 offset:2048
	ds_read_b128 v[22:25], v192
	ds_read_b128 v[30:33], v192 offset:2048
	ds_read_b128 v[2:5], v193
	ds_read_b128 v[10:13], v193 offset:2048
	ds_read_b128 v[6:9], v194
	ds_read_b128 v[14:17], v194 offset:2048
	s_add_u32 s22, s20, 0xfffc0080
	s_addc_u32 s23, s21, -1
	s_cmp_eq_u32 s55, 12
	s_cselect_b32 s25, s13, s23
	s_cselect_b32 s24, s45, s22
	s_cselect_b32 s23, s11, s54
	s_cselect_b32 s22, s52, s53
	s_add_i32 m0, s19, 0xc000
	ds_read_b128 v[178:181], v195
	ds_read_b128 v[198:201], v195 offset:2048
	ds_read_b128 v[182:185], v196
	ds_read_b128 v[202:205], v196 offset:2048
	ds_read_b128 v[206:209], v195 offset:4096
	ds_read_b128 v[214:217], v195 offset:6144
	ds_read_b128 v[210:213], v196 offset:4096
	ds_read_b128 v[218:221], v196 offset:6144
	global_load_lds_dwordx4 v170, s[20:21]
	s_add_i32 m0, s19, 0xe000
	s_nop 0
	global_load_lds_dwordx4 v172, s[20:21]
	s_waitcnt vmcnt(8)
	s_waitcnt lgkmcnt(0)
	s_barrier
	s_setprio 1
	s_waitcnt lgkmcnt(0)
	v_mfma_scale_f32_16x16x128_f8f6f4 v[158:161], v[18:25], v[178:185], v[158:161], v1, v186 op_sel_hi:[0,0,0]
	v_mfma_scale_f32_16x16x128_f8f6f4 v[150:153], v[26:33], v[178:185], v[150:153], v1, v186 op_sel_hi:[0,0,0]
	v_mfma_scale_f32_16x16x128_f8f6f4 v[142:145], v[18:25], v[198:205], v[142:145], v1, v186 op_sel_hi:[0,0,0]
	v_mfma_scale_f32_16x16x128_f8f6f4 v[134:137], v[26:33], v[198:205], v[134:137], v1, v186 op_sel_hi:[0,0,0]
	v_mfma_scale_f32_16x16x128_f8f6f4 v[126:129], v[18:25], v[206:213], v[126:129], v1, v186 op_sel_hi:[0,0,0]
	v_mfma_scale_f32_16x16x128_f8f6f4 v[118:121], v[26:33], v[206:213], v[118:121], v1, v186 op_sel_hi:[0,0,0]
	v_mfma_scale_f32_16x16x128_f8f6f4 v[110:113], v[18:25], v[214:221], v[110:113], v1, v186 op_sel_hi:[0,0,0]
	v_mfma_scale_f32_16x16x128_f8f6f4 v[102:105], v[26:33], v[214:221], v[102:105], v1, v186 op_sel_hi:[0,0,0]
	s_setprio 0
	s_setprio 1
	v_mfma_scale_f32_16x16x128_f8f6f4 v[154:157], v[2:9], v[178:185], v[154:157], v1, v186 op_sel_hi:[0,0,0]
	v_mfma_scale_f32_16x16x128_f8f6f4 v[146:149], v[10:17], v[178:185], v[146:149], v1, v186 op_sel_hi:[0,0,0]
	v_mfma_scale_f32_16x16x128_f8f6f4 v[138:141], v[2:9], v[198:205], v[138:141], v1, v186 op_sel_hi:[0,0,0]
	v_mfma_scale_f32_16x16x128_f8f6f4 v[130:133], v[10:17], v[198:205], v[130:133], v1, v186 op_sel_hi:[0,0,0]
	v_mfma_scale_f32_16x16x128_f8f6f4 v[122:125], v[2:9], v[206:213], v[122:125], v1, v186 op_sel_hi:[0,0,0]
	v_mfma_scale_f32_16x16x128_f8f6f4 v[114:117], v[10:17], v[206:213], v[114:117], v1, v186 op_sel_hi:[0,0,0]
	v_mfma_scale_f32_16x16x128_f8f6f4 v[106:109], v[2:9], v[214:221], v[106:109], v1, v186 op_sel_hi:[0,0,0]
	v_mfma_scale_f32_16x16x128_f8f6f4 v[98:101], v[10:17], v[214:221], v[98:101], v1, v186 op_sel_hi:[0,0,0]
	s_setprio 0
	s_barrier
	s_add_i32 s56, s41, s30
	s_mov_b32 m0, s56
	ds_read_b128 v[198:201], v195 offset:16384
	ds_read_b128 v[206:209], v195 offset:18432
	ds_read_b128 v[202:205], v196 offset:16384
	ds_read_b128 v[210:213], v196 offset:18432
	ds_read_b128 v[214:217], v195 offset:20480
	ds_read_b128 v[222:225], v195 offset:22528
	ds_read_b128 v[218:221], v196 offset:20480
	ds_read_b128 v[226:229], v196 offset:22528
	global_load_lds_dwordx4 v164, s[22:23]
	s_add_i32 m0, s56, 0x2000
	s_add_u32 s56, s22, 0x40000
	s_addc_u32 s57, s23, 0
	s_add_i32 s58, s42, s30
	global_load_lds_dwordx4 v168, s[22:23]
	s_mov_b32 m0, s58
	s_nop 0
	global_load_lds_dwordx4 v164, s[56:57]
	s_add_i32 m0, s58, 0x2000
	s_nop 0
	global_load_lds_dwordx4 v168, s[56:57]
	s_mov_b32 m0, s19
	s_nop 0
	global_load_lds_dwordx4 v162, s[24:25]
	s_mov_b32 m0, s34
	s_nop 0
	global_load_lds_dwordx4 v166, s[24:25]
	s_waitcnt vmcnt(8)
	s_waitcnt lgkmcnt(0)
	s_barrier
	s_setprio 1
	s_waitcnt lgkmcnt(0)
	v_mfma_scale_f32_16x16x128_f8f6f4 v[94:97], v[18:25], v[198:205], v[94:97], v1, v186 op_sel_hi:[0,0,0]
	v_mfma_scale_f32_16x16x128_f8f6f4 v[86:89], v[26:33], v[198:205], v[86:89], v1, v186 op_sel_hi:[0,0,0]
	v_mfma_scale_f32_16x16x128_f8f6f4 v[78:81], v[18:25], v[206:213], v[78:81], v1, v186 op_sel_hi:[0,0,0]
	v_mfma_scale_f32_16x16x128_f8f6f4 v[70:73], v[26:33], v[206:213], v[70:73], v1, v186 op_sel_hi:[0,0,0]
	v_mfma_scale_f32_16x16x128_f8f6f4 v[62:65], v[18:25], v[214:221], v[62:65], v1, v186 op_sel_hi:[0,0,0]
	v_mfma_scale_f32_16x16x128_f8f6f4 v[54:57], v[26:33], v[214:221], v[54:57], v1, v186 op_sel_hi:[0,0,0]
	v_mfma_scale_f32_16x16x128_f8f6f4 v[46:49], v[18:25], v[222:229], v[46:49], v1, v186 op_sel_hi:[0,0,0]
	v_mfma_scale_f32_16x16x128_f8f6f4 v[38:41], v[26:33], v[222:229], v[38:41], v1, v186 op_sel_hi:[0,0,0]
	s_setprio 0
	s_setprio 1
	v_mfma_scale_f32_16x16x128_f8f6f4 v[90:93], v[2:9], v[198:205], v[90:93], v1, v186 op_sel_hi:[0,0,0]
	v_mfma_scale_f32_16x16x128_f8f6f4 v[82:85], v[10:17], v[198:205], v[82:85], v1, v186 op_sel_hi:[0,0,0]
	v_mfma_scale_f32_16x16x128_f8f6f4 v[74:77], v[2:9], v[206:213], v[74:77], v1, v186 op_sel_hi:[0,0,0]
	v_mfma_scale_f32_16x16x128_f8f6f4 v[66:69], v[10:17], v[206:213], v[66:69], v1, v186 op_sel_hi:[0,0,0]
	v_mfma_scale_f32_16x16x128_f8f6f4 v[58:61], v[2:9], v[214:221], v[58:61], v1, v186 op_sel_hi:[0,0,0]
	v_mfma_scale_f32_16x16x128_f8f6f4 v[50:53], v[10:17], v[214:221], v[50:53], v1, v186 op_sel_hi:[0,0,0]
	v_mfma_scale_f32_16x16x128_f8f6f4 v[42:45], v[2:9], v[222:229], v[42:45], v1, v186 op_sel_hi:[0,0,0]
	v_mfma_scale_f32_16x16x128_f8f6f4 v[34:37], v[10:17], v[222:229], v[34:37], v1, v186 op_sel_hi:[0,0,0]
	s_setprio 0
	s_barrier
; #define PG8_STAGE(bufoff, gbase, voff) do { _Pragma("unroll") for (int _i = 0; _i < 2; ++_i) \
;         __builtin_amdgcn_global_load_lds((const unsigned*)((const char*)(gbase) + (voff)[_i]), (PG8_LAS unsigned*)(lds + (bufoff) + ldsw + _i * 8192), 16, 0, 0); } while (0)
; #define PG8_LDA(dst, b, h) do { _Pragma("unroll") for (int m = 0; m < 4; ++m) _Pragma("unroll") for (int k = 0; k < 2; ++k) dst[m][k] = *(const PG8_LAS bf16x8*)(lds + PG8_SA(b, h) + aoff + m * 2048 + k * 1024); } while (0)
; #define PG8_LDB(dst, b, h) do { _Pragma("unroll") for (int n = 0; n < 2; ++n) _Pragma("unroll") for (int k = 0; k < 2; ++k) dst[n][k] = *(const PG8_LAS bf16x8*)(lds + PG8_SB(b, h) + boff + n * 2048 + k * 1024); } while (0)
; #define PG8_MMA(ai, bj, At, Bt) do { __builtin_amdgcn_s_setprio(1); _Pragma("unroll") for (int m = 0; m < 4; ++m) _Pragma("unroll") for (int n = 0; n < 2; ++n) _Pragma("unroll") for (int k = 0; k < 2; ++k) \
;         acc[ai][bj][m][n] = __builtin_amdgcn_mfma_f32_16x16x32_bf16(Bt[n][k], At[m][k], acc[ai][bj][m][n], 0, 0, 0); __builtin_amdgcn_s_setprio(0); } while (0)
; #define PG8_WAIT_V(n) asm volatile("s_waitcnt vmcnt(" #n ")" ::: "memory")
; #define PG8_WAIT_L(n) asm volatile("s_waitcnt lgkmcnt(" #n ")" ::: "memory")
; #define PG8_BAR __builtin_amdgcn_s_barrier()
; #define PG8_SCHED __builtin_amdgcn_sched_barrier(0)
; #define PG8_STAGE(bufoff, gbase, voff) do { _Pragma("unroll") for (int _i = 0; _i < 2; ++_i) \
;         __builtin_amdgcn_global_load_lds((const unsigned*)((const char*)(gbase) + (voff)[_i]), (PG8_LAS unsigned*)(lds + (bufoff) + ldsw + _i * 8192), 16, 0, 0); } while (0)
; #define PG8_BAR __builtin_amdgcn_s_barrier()
; template <class Epi, class Sched, bool ALIGN_EPI = false>
; __device__ __forceinline__ void gemm_phase8(PG8_LAS unsigned char* lds, const Gemm g, const Sched& S, const Epi& E) {
;     ...
;             PG8_LDB(B0, 1, 0); PG8_LDB(B1, 1, 1); PG8_SCHED; PG8_LDA(At, 1, 0); PG8_STAGE(PG8_SA(0, 1), a2 + hstepA, voffA);
;             PG8_WAIT_V(8); PG8_WAIT_L(0); PG8_BAR; PG8_MMA(0, 0, At, B0); PG8_MMA(0, 1, At, B1); PG8_BAR; PG8_SCHED;
;             PG8_LDA(At, 1, 1); PG8_STAGE(PG8_SB(1, 0), b3, voffB); PG8_STAGE(PG8_SB(1, 1), b3 + hstepB, voffB); PG8_STAGE(PG8_SA(1, 0), a3, voffA);
;             PG8_WAIT_V(8); PG8_WAIT_L(0); PG8_BAR; PG8_MMA(1, 0, At, B0); PG8_MMA(1, 1, At, B1); PG8_BAR; PG8_SCHED;
;         }
	s_add_i32 s56, 0, 0x18000
	s_add_i32 s57, 0, 0x1c000
	v_add_u32_e32 v6, s56, v187
	v_add_u32_e32 v14, s56, v188
	v_add_u32_e32 v22, s57, v187
	v_add_u32_e32 v30, s57, v188
	ds_read_b128 v[2:5], v6
	ds_read_b128 v[10:13], v6 offset:2048
	ds_read_b128 v[6:9], v14
	ds_read_b128 v[14:17], v14 offset:2048
	ds_read_b128 v[18:21], v22
	ds_read_b128 v[26:29], v22 offset:2048
	ds_read_b128 v[22:25], v30
	ds_read_b128 v[30:33], v30 offset:2048
	s_add_u32 s24, s24, 0x40000
	s_addc_u32 s25, s25, 0
	s_mov_b32 m0, s35
	ds_read_b128 v[198:201], v195 offset:32768
	ds_read_b128 v[206:209], v195 offset:34816
	ds_read_b128 v[202:205], v196 offset:32768
	ds_read_b128 v[210:213], v196 offset:34816
	ds_read_b128 v[214:217], v195 offset:36864
	ds_read_b128 v[222:225], v195 offset:38912
	ds_read_b128 v[218:221], v196 offset:36864
	ds_read_b128 v[226:229], v196 offset:38912
	global_load_lds_dwordx4 v162, s[24:25]
	s_mov_b32 m0, s36
	s_nop 0
	global_load_lds_dwordx4 v166, s[24:25]
	s_waitcnt vmcnt(8)
	s_waitcnt lgkmcnt(0)
	s_barrier
	s_setprio 1
	s_waitcnt lgkmcnt(0)
	v_mfma_scale_f32_16x16x128_f8f6f4 v[158:161], v[2:9], v[198:205], v[158:161], v1, v186 op_sel_hi:[0,0,0]
	v_mfma_scale_f32_16x16x128_f8f6f4 v[150:153], v[10:17], v[198:205], v[150:153], v1, v186 op_sel_hi:[0,0,0]
	v_mfma_scale_f32_16x16x128_f8f6f4 v[142:145], v[2:9], v[206:213], v[142:145], v1, v186 op_sel_hi:[0,0,0]
	v_mfma_scale_f32_16x16x128_f8f6f4 v[134:137], v[10:17], v[206:213], v[134:137], v1, v186 op_sel_hi:[0,0,0]
	v_mfma_scale_f32_16x16x128_f8f6f4 v[126:129], v[2:9], v[214:221], v[126:129], v1, v186 op_sel_hi:[0,0,0]
	v_mfma_scale_f32_16x16x128_f8f6f4 v[118:121], v[10:17], v[214:221], v[118:121], v1, v186 op_sel_hi:[0,0,0]
	v_mfma_scale_f32_16x16x128_f8f6f4 v[110:113], v[2:9], v[222:229], v[110:113], v1, v186 op_sel_hi:[0,0,0]
	v_mfma_scale_f32_16x16x128_f8f6f4 v[102:105], v[10:17], v[222:229], v[102:105], v1, v186 op_sel_hi:[0,0,0]
	s_setprio 0
	s_setprio 1
	v_mfma_scale_f32_16x16x128_f8f6f4 v[154:157], v[18:25], v[198:205], v[154:157], v1, v186 op_sel_hi:[0,0,0]
	v_mfma_scale_f32_16x16x128_f8f6f4 v[146:149], v[26:33], v[198:205], v[146:149], v1, v186 op_sel_hi:[0,0,0]
	v_mfma_scale_f32_16x16x128_f8f6f4 v[138:141], v[18:25], v[206:213], v[138:141], v1, v186 op_sel_hi:[0,0,0]
	v_mfma_scale_f32_16x16x128_f8f6f4 v[130:133], v[26:33], v[206:213], v[130:133], v1, v186 op_sel_hi:[0,0,0]
	v_mfma_scale_f32_16x16x128_f8f6f4 v[122:125], v[18:25], v[214:221], v[122:125], v1, v186 op_sel_hi:[0,0,0]
	v_mfma_scale_f32_16x16x128_f8f6f4 v[114:117], v[26:33], v[214:221], v[114:117], v1, v186 op_sel_hi:[0,0,0]
	v_mfma_scale_f32_16x16x128_f8f6f4 v[106:109], v[18:25], v[222:229], v[106:109], v1, v186 op_sel_hi:[0,0,0]
	v_mfma_scale_f32_16x16x128_f8f6f4 v[98:101], v[26:33], v[222:229], v[98:101], v1, v186 op_sel_hi:[0,0,0]
	s_setprio 0
	s_barrier
	s_add_i32 s101, s56, s30
	s_add_u32 s98, s22, s6
	s_addc_u32 s99, s23, s7
	s_mov_b32 m0, s101
	ds_read_b128 v[198:201], v195 offset:49152
	ds_read_b128 v[206:209], v195 offset:51200
	ds_read_b128 v[202:205], v196 offset:49152
	ds_read_b128 v[210:213], v196 offset:51200
	ds_read_b128 v[214:217], v195 offset:53248
	ds_read_b128 v[222:225], v195 offset:55296
	ds_read_b128 v[218:221], v196 offset:53248
	ds_read_b128 v[226:229], v196 offset:55296
	global_load_lds_dwordx4 v164, s[98:99]
	s_add_i32 m0, s101, 0x2000
	s_add_u32 s22, s22, 0x40080
	s_addc_u32 s23, s23, 0
	s_add_i32 s101, s57, s30
	global_load_lds_dwordx4 v168, s[98:99]
	s_add_u32 s98, s24, s6
	s_addc_u32 s99, s25, s7
	s_sub_u32 s98, s98, 0x40000
	s_subb_u32 s99, s99, 0
	s_mov_b32 m0, s101
	s_nop 0
	global_load_lds_dwordx4 v164, s[22:23]
	s_add_i32 m0, s101, 0x2000
	s_nop 0
	global_load_lds_dwordx4 v168, s[22:23]
	s_mov_b32 m0, s39
	s_nop 0
	global_load_lds_dwordx4 v162, s[98:99]
	s_mov_b32 m0, s40
	s_nop 0
	global_load_lds_dwordx4 v166, s[98:99]
	s_waitcnt vmcnt(8)
	s_waitcnt lgkmcnt(0)
	s_barrier
	s_setprio 1
	s_waitcnt lgkmcnt(0)
	v_mfma_scale_f32_16x16x128_f8f6f4 v[94:97], v[2:9], v[198:205], v[94:97], v1, v186 op_sel_hi:[0,0,0]
	v_mfma_scale_f32_16x16x128_f8f6f4 v[86:89], v[10:17], v[198:205], v[86:89], v1, v186 op_sel_hi:[0,0,0]
	v_mfma_scale_f32_16x16x128_f8f6f4 v[78:81], v[2:9], v[206:213], v[78:81], v1, v186 op_sel_hi:[0,0,0]
	v_mfma_scale_f32_16x16x128_f8f6f4 v[70:73], v[10:17], v[206:213], v[70:73], v1, v186 op_sel_hi:[0,0,0]
	v_mfma_scale_f32_16x16x128_f8f6f4 v[62:65], v[2:9], v[214:221], v[62:65], v1, v186 op_sel_hi:[0,0,0]
	v_mfma_scale_f32_16x16x128_f8f6f4 v[54:57], v[10:17], v[214:221], v[54:57], v1, v186 op_sel_hi:[0,0,0]
	v_mfma_scale_f32_16x16x128_f8f6f4 v[46:49], v[2:9], v[222:229], v[46:49], v1, v186 op_sel_hi:[0,0,0]
	v_mfma_scale_f32_16x16x128_f8f6f4 v[38:41], v[10:17], v[222:229], v[38:41], v1, v186 op_sel_hi:[0,0,0]
	s_setprio 0
	s_setprio 1
	v_mfma_scale_f32_16x16x128_f8f6f4 v[90:93], v[18:25], v[198:205], v[90:93], v1, v186 op_sel_hi:[0,0,0]
	v_mfma_scale_f32_16x16x128_f8f6f4 v[82:85], v[26:33], v[198:205], v[82:85], v1, v186 op_sel_hi:[0,0,0]
	v_mfma_scale_f32_16x16x128_f8f6f4 v[74:77], v[18:25], v[206:213], v[74:77], v1, v186 op_sel_hi:[0,0,0]
	v_mfma_scale_f32_16x16x128_f8f6f4 v[66:69], v[26:33], v[206:213], v[66:69], v1, v186 op_sel_hi:[0,0,0]
	v_mfma_scale_f32_16x16x128_f8f6f4 v[58:61], v[18:25], v[214:221], v[58:61], v1, v186 op_sel_hi:[0,0,0]
	v_mfma_scale_f32_16x16x128_f8f6f4 v[50:53], v[26:33], v[214:221], v[50:53], v1, v186 op_sel_hi:[0,0,0]
	v_mfma_scale_f32_16x16x128_f8f6f4 v[42:45], v[18:25], v[222:229], v[42:45], v1, v186 op_sel_hi:[0,0,0]
	v_mfma_scale_f32_16x16x128_f8f6f4 v[34:37], v[26:33], v[222:229], v[34:37], v1, v186 op_sel_hi:[0,0,0]
	s_setprio 0
	s_barrier
	s_add_i32 s55, s55, 2
	s_add_u32 s20, s20, 0x100
	s_addc_u32 s21, s21, 0
	s_add_u32 s53, s53, 0x100
	s_addc_u32 s54, s54, 0
	s_cmp_gt_u32 s55, 13
	s_cbranch_scc0 .LBB0_1422
	s_and_b64 vcc, exec, s[8:9]
	s_cbranch_vccz .LBB0_1425
	s_barrier
	.p2align	6

; template <class Epi, class Sched, bool ALIGN_EPI = false>
; __device__ __forceinline__ void gemm_phase8(PG8_LAS unsigned char* lds, const Gemm g, const Sched& S, const Epi& E) {
;     ...
;     for (;;) {
;         const bool has_next = S.next(ui + 1, nxt);
;         const size_t nko = (has_next && nxt.kp > 0) ? (size_t)nxt.kp * g.kpiece : 0;
;         const char* nA = has_next ? (const char*)g.A + (size_t)nxt.pm * tstepA + (size_t)nxt.pn * astep + nko : cA; const char* nB = has_next ? (const char*)g.Bt + (size_t)nxt.pn * tstepB + nko : cB;
.LBB0_1501:
	s_andn2_b64 vcc, exec, s[2:3]
	s_mov_b32 s77, s75
	s_mov_b32 s78, s76
	s_mov_b32 s30, s0
	s_mov_b64 s[34:35], s[28:29]
	s_mov_b64 s[38:39], s[26:27]
	s_cbranch_vccz .LBB0_1521
	.p2align	6
